# P16 final norm: gain vector loaded once, one counted wait per row pair (same restructure as P6/P9/P13)
# speedup vs baseline: 1.0057x; 1.0027x over previous
.LBB0_1449:
	s_and_b64 s[4:5], s[4:5], s[6:7]
	s_andn2_b64 vcc, exec, s[4:5]
	s_cbranch_vccnz .LBB0_1466
	s_waitcnt vmcnt(0)
	v_mov_b32_e32 v0, s1
	v_mov_b32_e32 v3, s0
	v_readfirstlane_b32 s3, v254
	s_lshl_b32 s2, s2, 3
	s_ashr_i32 s3, s3, 6
	s_add_i32 s14, s3, s2
	v_readfirstlane_b32 s2, v3
	v_mov_b32_e32 v3, s1
	v_mov_b32_e32 v4, s0
	v_mov_b32_e32 v1, s0
	v_mov_b32_e32 v2, s0
	v_readfirstlane_b32 s3, v0
	v_mov_b32_e32 v0, s1
	v_readfirstlane_b32 s7, v3
	v_mov_b32_e32 v3, s1
	v_readfirstlane_b32 s6, v4
	s_cmpk_gt_i32 s14, 0x7fff
	v_readfirstlane_b32 s0, v2
	v_readfirstlane_b32 s1, v3
	v_readfirstlane_b32 s4, v1
	v_readfirstlane_b32 s5, v0
	s_cbranch_scc1 .LBB0_1466
	s_load_dwordx2 s[8:9], s[2:3], 0xc0
	s_load_dwordx2 s[10:11], s[6:7], 0xc0
	s_waitcnt lgkmcnt(0)
	s_lshl_b32 s12, s33, 3
	v_and_b32_e32 v4, 63, v254
	s_lshl_b32 s20, s33, 4
	s_add_i32 s2, s14, s12
	v_lshlrev_b32_e32 v0, 3, v4
	v_mov_b32_e32 v1, 0
	s_cmp_lt_i32 s2, 0x8000
	v_lshl_add_u64 v[2:3], s[8:9], 0, v[0:1]
	s_mov_b64 s[6:7], 0x4000000
	s_cselect_b32 s2, s2, s14
	v_lshl_add_u64 v[18:19], v[2:3], 0, s[6:7]
	v_lshl_add_u64 v[2:3], s[10:11], 0, v[0:1]
	s_mov_b64 s[6:7], 0x8000000
	s_ashr_i32 s15, s14, 31
	v_lshl_add_u64 v[20:21], v[2:3], 0, s[6:7]
	s_lshl_b64 s[6:7], s[14:15], 11
	v_lshl_add_u64 v[2:3], v[18:19], 0, s[6:7]
	s_ashr_i32 s3, s2, 31
	global_load_dwordx2 v[22:23], v[2:3], off
	global_load_dwordx2 v[24:25], v[2:3], off offset:512
	global_load_dwordx2 v[26:27], v[2:3], off offset:1024
	global_load_dwordx2 v[28:29], v[2:3], off offset:1536
	v_lshl_add_u64 v[2:3], v[20:21], 0, s[6:7]
	s_lshl_b64 s[6:7], s[2:3], 11
	global_load_dwordx2 v[30:31], v[2:3], off
	global_load_dwordx2 v[32:33], v[2:3], off offset:512
	global_load_dwordx2 v[34:35], v[2:3], off offset:1024
	global_load_dwordx2 v[36:37], v[2:3], off offset:1536
	v_lshl_add_u64 v[2:3], v[18:19], 0, s[6:7]
	global_load_dwordx2 v[42:43], v[2:3], off
	global_load_dwordx2 v[44:45], v[2:3], off offset:512
	global_load_dwordx2 v[46:47], v[2:3], off offset:1024
	global_load_dwordx2 v[48:49], v[2:3], off offset:1536
	v_lshl_add_u64 v[2:3], v[20:21], 0, s[6:7]
	global_load_dwordx2 v[50:51], v[2:3], off
	global_load_dwordx2 v[52:53], v[2:3], off offset:512
	global_load_dwordx2 v[54:55], v[2:3], off offset:1024
	global_load_dwordx2 v[56:57], v[2:3], off offset:1536
	s_load_dwordx2 s[6:7], s[4:5], 0xb8
	s_load_dwordx2 s[8:9], s[0:1], 0x28
	v_lshlrev_b32_e32 v0, 4, v4
	s_mov_b64 s[0:1], 0x1000
	s_mul_i32 s21, s33, 40
	s_waitcnt lgkmcnt(0)
	v_lshl_add_u64 v[40:41], s[6:7], 0, v[0:1]
	v_lshl_add_u64 v[2:3], s[8:9], 0, v[0:1]
	v_mbcnt_lo_u32_b32 v0, -1, 0
	v_mbcnt_hi_u32_b32 v0, -1, v0
	v_and_b32_e32 v1, 64, v0
	v_lshl_add_u64 v[38:39], v[2:3], 0, s[0:1]
	v_add_u32_e32 v1, 64, v1
	v_xor_b32_e32 v2, 1, v0
	v_cmp_lt_i32_e32 vcc, v2, v1
	s_cmp_lg_u64 s[6:7], 0
	s_cselect_b64 s[4:5], -1, 0
	v_cndmask_b32_e32 v2, v0, v2, vcc
	v_lshlrev_b32_e32 v88, 2, v2
	v_xor_b32_e32 v2, 2, v0
	v_cmp_lt_i32_e32 vcc, v2, v1
	s_lshl_b32 s15, s33, 5
	s_mul_i32 s22, s33, 24
	v_cndmask_b32_e32 v2, v0, v2, vcc
	v_lshlrev_b32_e32 v89, 2, v2
	v_xor_b32_e32 v2, 4, v0
	v_cmp_lt_i32_e32 vcc, v2, v1
	v_mov_b32_e32 v94, 0x358637bd
	s_mov_b32 s10, s14
	v_cndmask_b32_e32 v2, v0, v2, vcc
	v_lshlrev_b32_e32 v90, 2, v2
	v_xor_b32_e32 v2, 8, v0
	v_cmp_lt_i32_e32 vcc, v2, v1
	s_nop 1
	v_cndmask_b32_e32 v2, v0, v2, vcc
	v_lshlrev_b32_e32 v91, 2, v2
	v_xor_b32_e32 v2, 16, v0
	v_cmp_lt_i32_e32 vcc, v2, v1
	s_nop 1
	v_cndmask_b32_e32 v2, v0, v2, vcc
	v_lshlrev_b32_e32 v92, 2, v2
	v_xor_b32_e32 v2, 32, v0
	v_cmp_lt_i32_e32 vcc, v2, v1
	s_nop 1
	v_cndmask_b32_e32 v0, v0, v2, vcc
	v_lshlrev_b32_e32 v93, 2, v0
	global_load_dwordx4 v[98:101], v[38:39], off offset:3072
	global_load_dwordx4 v[102:105], v[38:39], off offset:2048
	global_load_dwordx4 v[106:109], v[38:39], off
	global_load_dwordx4 v[110:113], v[38:39], off offset:1024
	s_waitcnt vmcnt(0)
	s_branch .LBB0_1453

.LBB0_1453:
	s_waitcnt vmcnt(8)
	s_add_i32 s12, s14, s20
	s_cmp_lt_i32 s12, 0x8000
	s_cselect_b64 s[16:17], -1, 0
	s_cmpk_gt_i32 s12, 0x7fff
	s_cbranch_scc1 .LBB0_1455
	s_add_i32 s0, s22, s14
	s_cmp_lt_i32 s0, 0x8000
	s_cselect_b32 s6, s0, s12
	s_ashr_i32 s13, s12, 31
	s_lshl_b64 s[0:1], s[12:13], 11
	v_lshl_add_u64 v[8:9], v[18:19], 0, s[0:1]
	s_ashr_i32 s7, s6, 31
	global_load_dwordx2 v[0:1], v[8:9], off
	global_load_dwordx2 v[2:3], v[8:9], off offset:512
	global_load_dwordx2 v[4:5], v[8:9], off offset:1024
	global_load_dwordx2 v[6:7], v[8:9], off offset:1536
	v_lshl_add_u64 v[8:9], v[20:21], 0, s[0:1]
	s_lshl_b64 s[0:1], s[6:7], 11
	v_lshl_add_u64 v[64:65], v[18:19], 0, s[0:1]
	v_lshl_add_u64 v[72:73], v[20:21], 0, s[0:1]
	global_load_dwordx2 v[16:17], v[8:9], off
	global_load_dwordx2 v[58:59], v[8:9], off offset:512
	global_load_dwordx2 v[60:61], v[8:9], off offset:1024
	global_load_dwordx2 v[62:63], v[8:9], off offset:1536
	s_nop 0
	global_load_dwordx2 v[8:9], v[64:65], off
	global_load_dwordx2 v[10:11], v[64:65], off offset:512
	global_load_dwordx2 v[12:13], v[64:65], off offset:1024
	global_load_dwordx2 v[14:15], v[64:65], off offset:1536
	s_nop 0
	global_load_dwordx2 v[64:65], v[72:73], off
	global_load_dwordx2 v[66:67], v[72:73], off offset:512
	global_load_dwordx2 v[68:69], v[72:73], off offset:1024
	global_load_dwordx2 v[70:71], v[72:73], off offset:1536
	s_mov_b32 s8, s12
.LBB0_1455:
	s_nop 0
	v_and_b32_e32 v73, 0xffff0000, v30
	v_and_b32_e32 v75, 0xffff0000, v31
	v_lshlrev_b32_e32 v72, 16, v30
	v_lshlrev_b32_e32 v74, 16, v31
	v_mul_f32_e32 v76, v73, v73
	v_mul_f32_e32 v77, v75, v75
	v_fmac_f32_e32 v76, v72, v72
	v_fmac_f32_e32 v77, v74, v74
	v_add_f32_e32 v80, v76, v77
	s_nop 0
	v_and_b32_e32 v77, 0xffff0000, v32
	v_and_b32_e32 v79, 0xffff0000, v33
	v_lshlrev_b32_e32 v76, 16, v32
	v_lshlrev_b32_e32 v78, 16, v33
	v_mul_f32_e32 v81, v77, v77
	v_mul_f32_e32 v82, v79, v79
	v_fmac_f32_e32 v81, v76, v76
	v_fmac_f32_e32 v82, v78, v78
	v_add_f32_e32 v81, v81, v82
	v_add_f32_e32 v84, v80, v81
	s_nop 0
	v_and_b32_e32 v81, 0xffff0000, v34
	v_and_b32_e32 v83, 0xffff0000, v35
	v_lshlrev_b32_e32 v80, 16, v34
	v_lshlrev_b32_e32 v82, 16, v35
	v_mul_f32_e32 v85, v81, v81
	v_mul_f32_e32 v86, v83, v83
	v_fmac_f32_e32 v85, v80, v80
	v_fmac_f32_e32 v86, v82, v82
	v_add_f32_e32 v85, v85, v86
	v_add_f32_e32 v95, v85, v84
	s_nop 0
	v_and_b32_e32 v85, 0xffff0000, v36
	v_and_b32_e32 v87, 0xffff0000, v37
	v_lshlrev_b32_e32 v84, 16, v36
	v_lshlrev_b32_e32 v86, 16, v37
	s_waitcnt lgkmcnt(0)
	v_mul_f32_e32 v96, v85, v85
	v_mul_f32_e32 v97, v87, v87
	v_fmac_f32_e32 v96, v84, v84
	v_fmac_f32_e32 v97, v86, v86
	v_add_f32_e32 v96, v96, v97
	v_add_f32_e32 v95, v96, v95
	ds_bpermute_b32 v96, v88, v95
	v_cndmask_b32_e64 v97, 0, 1, s[4:5]
	v_cmp_ne_u32_e64 s[0:1], 1, v97
	s_andn2_b64 vcc, exec, s[4:5]
	s_waitcnt lgkmcnt(0)
	v_add_f32_e32 v95, v95, v96
	ds_bpermute_b32 v96, v89, v95
	s_waitcnt lgkmcnt(0)
	v_add_f32_e32 v95, v95, v96
	ds_bpermute_b32 v96, v90, v95
	s_waitcnt lgkmcnt(0)
	v_add_f32_e32 v95, v95, v96
	ds_bpermute_b32 v96, v91, v95
	s_waitcnt lgkmcnt(0)
	v_add_f32_e32 v95, v95, v96
	ds_bpermute_b32 v96, v92, v95
	s_waitcnt lgkmcnt(0)
	v_add_f32_e32 v95, v95, v96
	ds_bpermute_b32 v96, v93, v95
	s_cbranch_vccnz .LBB0_1457
	s_waitcnt lgkmcnt(0)
	v_add_f32_e32 v95, v95, v96
	v_fmamk_f32 v95, v95, 0x3a800000, v94
	v_rsq_f32_e32 v128, v95
	s_ashr_i32 s11, s10, 31
	v_lshlrev_b32_e32 v116, 16, v26
	v_and_b32_e32 v117, 0xffff0000, v26
	v_lshlrev_b32_e32 v118, 16, v27
	v_and_b32_e32 v119, 0xffff0000, v27
	v_lshlrev_b32_e32 v120, 16, v22
	v_and_b32_e32 v121, 0xffff0000, v22
	v_lshlrev_b32_e32 v122, 16, v23
	v_and_b32_e32 v123, 0xffff0000, v23
	s_lshl_b64 s[18:19], s[10:11], 12
	v_pk_mul_f32 v[80:81], v[80:81], v[128:129] op_sel_hi:[1,0]
	v_pk_mul_f32 v[82:83], v[82:83], v[128:129] op_sel_hi:[1,0]
	v_pk_mul_f32 v[132:133], v[72:73], v[128:129] op_sel_hi:[1,0]
	v_pk_mul_f32 v[134:135], v[74:75], v[128:129] op_sel_hi:[1,0]
	v_lshlrev_b32_e32 v96, 16, v28
	v_and_b32_e32 v97, 0xffff0000, v28
	v_lshlrev_b32_e32 v114, 16, v29
	v_and_b32_e32 v115, 0xffff0000, v29
	v_lshlrev_b32_e32 v124, 16, v24
	v_and_b32_e32 v125, 0xffff0000, v24
	v_lshlrev_b32_e32 v126, 16, v25
	v_and_b32_e32 v127, 0xffff0000, v25
	v_lshl_add_u64 v[130:131], v[40:41], 0, s[18:19]
	v_pk_mul_f32 v[84:85], v[84:85], v[128:129] op_sel_hi:[1,0]
	v_pk_mul_f32 v[86:87], v[86:87], v[128:129] op_sel_hi:[1,0]
	v_pk_mul_f32 v[136:137], v[76:77], v[128:129] op_sel_hi:[1,0]
	v_pk_mul_f32 v[128:129], v[78:79], v[128:129] op_sel_hi:[1,0]
	s_nop 0
	v_pk_fma_f32 v[74:75], v[86:87], v[100:101], v[114:115]
	s_nop 0
	v_pk_fma_f32 v[78:79], v[82:83], v[104:105], v[118:119]
	v_pk_fma_f32 v[76:77], v[80:81], v[102:103], v[116:117]
	s_nop 0
	v_pk_fma_f32 v[82:83], v[134:135], v[108:109], v[122:123]
	v_pk_fma_f32 v[80:81], v[132:133], v[106:107], v[120:121]
	v_pk_fma_f32 v[72:73], v[84:85], v[98:99], v[96:97]
	s_nop 0
	v_pk_fma_f32 v[86:87], v[128:129], v[112:113], v[126:127]
	v_pk_fma_f32 v[84:85], v[136:137], v[110:111], v[124:125]
	global_store_dwordx4 v[130:131], v[80:83], off
	global_store_dwordx4 v[130:131], v[84:87], off offset:1024
	global_store_dwordx4 v[130:131], v[76:79], off offset:2048
	global_store_dwordx4 v[130:131], v[72:75], off offset:3072
.LBB0_1457:
	s_nop 0
	s_nop 0
	v_and_b32_e32 v73, 0xffff0000, v50
	v_and_b32_e32 v75, 0xffff0000, v51
	v_lshlrev_b32_e32 v72, 16, v50
	v_lshlrev_b32_e32 v74, 16, v51
	v_mul_f32_e32 v76, v73, v73
	v_mul_f32_e32 v77, v75, v75
	v_fmac_f32_e32 v76, v72, v72
	v_fmac_f32_e32 v77, v74, v74
	v_add_f32_e32 v80, v76, v77
	s_nop 0
	v_and_b32_e32 v77, 0xffff0000, v52
	v_and_b32_e32 v79, 0xffff0000, v53
	v_lshlrev_b32_e32 v76, 16, v52
	v_lshlrev_b32_e32 v78, 16, v53
	v_mul_f32_e32 v81, v77, v77
	v_mul_f32_e32 v82, v79, v79
	v_fmac_f32_e32 v81, v76, v76
	v_fmac_f32_e32 v82, v78, v78
	v_add_f32_e32 v81, v81, v82
	v_add_f32_e32 v84, v80, v81
	s_nop 0
	v_and_b32_e32 v81, 0xffff0000, v54
	v_and_b32_e32 v83, 0xffff0000, v55
	v_lshlrev_b32_e32 v80, 16, v54
	v_lshlrev_b32_e32 v82, 16, v55
	v_mul_f32_e32 v85, v81, v81
	v_mul_f32_e32 v86, v83, v83
	v_fmac_f32_e32 v85, v80, v80
	v_fmac_f32_e32 v86, v82, v82
	v_add_f32_e32 v85, v85, v86
	v_add_f32_e32 v95, v85, v84
	s_nop 0
	v_and_b32_e32 v85, 0xffff0000, v56
	v_and_b32_e32 v87, 0xffff0000, v57
	v_lshlrev_b32_e32 v84, 16, v56
	v_lshlrev_b32_e32 v86, 16, v57
	s_waitcnt lgkmcnt(0)
	v_mul_f32_e32 v96, v85, v85
	v_mul_f32_e32 v97, v87, v87
	v_fmac_f32_e32 v96, v84, v84
	v_fmac_f32_e32 v97, v86, v86
	v_add_f32_e32 v96, v96, v97
	v_add_f32_e32 v95, v96, v95
	ds_bpermute_b32 v96, v88, v95
	s_and_b64 vcc, exec, s[0:1]
	s_waitcnt lgkmcnt(0)
	v_add_f32_e32 v95, v95, v96
	ds_bpermute_b32 v96, v89, v95
	s_waitcnt lgkmcnt(0)
	v_add_f32_e32 v95, v95, v96
	ds_bpermute_b32 v96, v90, v95
	s_waitcnt lgkmcnt(0)
	v_add_f32_e32 v95, v95, v96
	ds_bpermute_b32 v96, v91, v95
	s_waitcnt lgkmcnt(0)
	v_add_f32_e32 v95, v95, v96
	ds_bpermute_b32 v96, v92, v95
	s_waitcnt lgkmcnt(0)
	v_add_f32_e32 v95, v95, v96
	ds_bpermute_b32 v96, v93, v95
	s_cbranch_vccnz .LBB0_1459
	s_waitcnt lgkmcnt(0)
	v_add_f32_e32 v95, v95, v96
	v_fmamk_f32 v95, v95, 0x3a800000, v94
	v_rsq_f32_e32 v128, v95
	s_ashr_i32 s3, s2, 31
	v_lshlrev_b32_e32 v116, 16, v46
	v_and_b32_e32 v117, 0xffff0000, v46
	v_lshlrev_b32_e32 v118, 16, v47
	v_and_b32_e32 v119, 0xffff0000, v47
	v_lshlrev_b32_e32 v120, 16, v42
	v_and_b32_e32 v121, 0xffff0000, v42
	v_lshlrev_b32_e32 v122, 16, v43
	v_and_b32_e32 v123, 0xffff0000, v43
	s_lshl_b64 s[18:19], s[2:3], 12
	v_pk_mul_f32 v[80:81], v[80:81], v[128:129] op_sel_hi:[1,0]
	v_pk_mul_f32 v[82:83], v[82:83], v[128:129] op_sel_hi:[1,0]
	v_pk_mul_f32 v[132:133], v[72:73], v[128:129] op_sel_hi:[1,0]
	v_pk_mul_f32 v[134:135], v[74:75], v[128:129] op_sel_hi:[1,0]
	v_lshlrev_b32_e32 v96, 16, v48
	v_and_b32_e32 v97, 0xffff0000, v48
	v_lshlrev_b32_e32 v114, 16, v49
	v_and_b32_e32 v115, 0xffff0000, v49
	v_lshlrev_b32_e32 v124, 16, v44
	v_and_b32_e32 v125, 0xffff0000, v44
	v_lshlrev_b32_e32 v126, 16, v45
	v_and_b32_e32 v127, 0xffff0000, v45
	v_lshl_add_u64 v[130:131], v[40:41], 0, s[18:19]
	v_pk_mul_f32 v[84:85], v[84:85], v[128:129] op_sel_hi:[1,0]
	v_pk_mul_f32 v[86:87], v[86:87], v[128:129] op_sel_hi:[1,0]
	v_pk_mul_f32 v[136:137], v[76:77], v[128:129] op_sel_hi:[1,0]
	v_pk_mul_f32 v[128:129], v[78:79], v[128:129] op_sel_hi:[1,0]
	s_nop 0
	v_pk_fma_f32 v[74:75], v[86:87], v[100:101], v[114:115]
	s_nop 0
	v_pk_fma_f32 v[78:79], v[82:83], v[104:105], v[118:119]
	v_pk_fma_f32 v[76:77], v[80:81], v[102:103], v[116:117]
	s_nop 0
	v_pk_fma_f32 v[82:83], v[134:135], v[108:109], v[122:123]
	v_pk_fma_f32 v[80:81], v[132:133], v[106:107], v[120:121]
	v_pk_fma_f32 v[72:73], v[84:85], v[98:99], v[96:97]
	s_nop 0
	v_pk_fma_f32 v[86:87], v[128:129], v[112:113], v[126:127]
	v_pk_fma_f32 v[84:85], v[136:137], v[110:111], v[124:125]
	global_store_dwordx4 v[130:131], v[80:83], off
	global_store_dwordx4 v[130:131], v[84:87], off offset:1024
	global_store_dwordx4 v[130:131], v[76:79], off offset:2048
	global_store_dwordx4 v[130:131], v[72:75], off offset:3072
.LBB0_1459:
	s_waitcnt vmcnt(8)
	s_add_i32 s18, s15, s14
	s_cmpk_gt_i32 s18, 0x7fff
	s_cbranch_scc1 .LBB0_1461
	s_add_i32 s2, s21, s14
	s_cmp_lt_i32 s2, 0x8000
	s_cselect_b32 s2, s2, s18
	s_ashr_i32 s19, s18, 31
	s_lshl_b64 s[10:11], s[18:19], 11
	s_ashr_i32 s3, s2, 31
	v_lshl_add_u64 v[30:31], v[18:19], 0, s[10:11]
	v_lshl_add_u64 v[42:43], v[20:21], 0, s[10:11]
	s_lshl_b64 s[10:11], s[2:3], 11
	v_lshl_add_u64 v[50:51], v[18:19], 0, s[10:11]
	v_lshl_add_u64 v[72:73], v[20:21], 0, s[10:11]
	global_load_dwordx2 v[22:23], v[30:31], off
	global_load_dwordx2 v[24:25], v[30:31], off offset:512
	global_load_dwordx2 v[26:27], v[30:31], off offset:1024
	global_load_dwordx2 v[28:29], v[30:31], off offset:1536
	s_nop 0
	global_load_dwordx2 v[30:31], v[42:43], off
	global_load_dwordx2 v[32:33], v[42:43], off offset:512
	global_load_dwordx2 v[34:35], v[42:43], off offset:1024
	global_load_dwordx2 v[36:37], v[42:43], off offset:1536
	s_nop 0
	global_load_dwordx2 v[42:43], v[50:51], off
	global_load_dwordx2 v[44:45], v[50:51], off offset:512
	global_load_dwordx2 v[46:47], v[50:51], off offset:1024
	global_load_dwordx2 v[48:49], v[50:51], off offset:1536
	s_nop 0
	global_load_dwordx2 v[50:51], v[72:73], off
	global_load_dwordx2 v[52:53], v[72:73], off offset:512
	global_load_dwordx2 v[54:55], v[72:73], off offset:1024
	global_load_dwordx2 v[56:57], v[72:73], off offset:1536
	s_mov_b32 s10, s18
.LBB0_1461:
	s_andn2_b64 vcc, exec, s[16:17]
	s_cbranch_vccnz .LBB0_1452
	v_and_b32_e32 v73, 0xffff0000, v16
	v_and_b32_e32 v75, 0xffff0000, v17
	v_lshlrev_b32_e32 v72, 16, v16
	v_lshlrev_b32_e32 v74, 16, v17
	v_mul_f32_e32 v76, v73, v73
	v_mul_f32_e32 v77, v75, v75
	v_fmac_f32_e32 v76, v72, v72
	v_fmac_f32_e32 v77, v74, v74
	v_add_f32_e32 v80, v76, v77
	v_and_b32_e32 v77, 0xffff0000, v58
	v_and_b32_e32 v79, 0xffff0000, v59
	v_lshlrev_b32_e32 v76, 16, v58
	v_lshlrev_b32_e32 v78, 16, v59
	v_mul_f32_e32 v81, v77, v77
	v_mul_f32_e32 v82, v79, v79
	v_fmac_f32_e32 v81, v76, v76
	v_fmac_f32_e32 v82, v78, v78
	v_add_f32_e32 v81, v81, v82
	v_add_f32_e32 v84, v81, v80
	v_and_b32_e32 v81, 0xffff0000, v60
	v_and_b32_e32 v83, 0xffff0000, v61
	v_lshlrev_b32_e32 v80, 16, v60
	v_lshlrev_b32_e32 v82, 16, v61
	v_mul_f32_e32 v85, v81, v81
	v_mul_f32_e32 v86, v83, v83
	v_fmac_f32_e32 v85, v80, v80
	v_fmac_f32_e32 v86, v82, v82
	v_add_f32_e32 v85, v85, v86
	v_add_f32_e32 v95, v85, v84
	v_and_b32_e32 v85, 0xffff0000, v62
	v_and_b32_e32 v87, 0xffff0000, v63
	v_lshlrev_b32_e32 v84, 16, v62
	v_lshlrev_b32_e32 v86, 16, v63
	s_waitcnt lgkmcnt(0)
	v_mul_f32_e32 v96, v85, v85
	v_mul_f32_e32 v97, v87, v87
	v_fmac_f32_e32 v96, v84, v84
	v_fmac_f32_e32 v97, v86, v86
	v_add_f32_e32 v96, v96, v97
	v_add_f32_e32 v95, v96, v95
	ds_bpermute_b32 v96, v88, v95
	s_and_b64 vcc, exec, s[0:1]
	s_waitcnt lgkmcnt(0)
	v_add_f32_e32 v95, v95, v96
	ds_bpermute_b32 v96, v89, v95
	s_waitcnt lgkmcnt(0)
	v_add_f32_e32 v95, v95, v96
	ds_bpermute_b32 v96, v90, v95
	s_waitcnt lgkmcnt(0)
	v_add_f32_e32 v95, v95, v96
	ds_bpermute_b32 v96, v91, v95
	s_waitcnt lgkmcnt(0)
	v_add_f32_e32 v95, v95, v96
	ds_bpermute_b32 v96, v92, v95
	s_waitcnt lgkmcnt(0)
	v_add_f32_e32 v95, v95, v96
	ds_bpermute_b32 v96, v93, v95
	s_cbranch_vccnz .LBB0_1464
	s_waitcnt lgkmcnt(0)
	v_add_f32_e32 v95, v95, v96
	v_fmamk_f32 v95, v95, 0x3a800000, v94
	v_rsq_f32_e32 v128, v95
	s_ashr_i32 s9, s8, 31
	v_lshlrev_b32_e32 v116, 16, v4
	v_and_b32_e32 v117, 0xffff0000, v4
	v_lshlrev_b32_e32 v118, 16, v5
	v_and_b32_e32 v119, 0xffff0000, v5
	v_lshlrev_b32_e32 v120, 16, v0
	v_and_b32_e32 v121, 0xffff0000, v0
	v_lshlrev_b32_e32 v122, 16, v1
	v_and_b32_e32 v123, 0xffff0000, v1
	s_lshl_b64 s[16:17], s[8:9], 12
	v_pk_mul_f32 v[80:81], v[80:81], v[128:129] op_sel_hi:[1,0]
	v_pk_mul_f32 v[82:83], v[82:83], v[128:129] op_sel_hi:[1,0]
	v_pk_mul_f32 v[132:133], v[72:73], v[128:129] op_sel_hi:[1,0]
	v_pk_mul_f32 v[134:135], v[74:75], v[128:129] op_sel_hi:[1,0]
	v_lshlrev_b32_e32 v96, 16, v6
	v_and_b32_e32 v97, 0xffff0000, v6
	v_lshlrev_b32_e32 v114, 16, v7
	v_and_b32_e32 v115, 0xffff0000, v7
	v_lshlrev_b32_e32 v124, 16, v2
	v_and_b32_e32 v125, 0xffff0000, v2
	v_lshlrev_b32_e32 v126, 16, v3
	v_and_b32_e32 v127, 0xffff0000, v3
	v_lshl_add_u64 v[130:131], v[40:41], 0, s[16:17]
	v_pk_mul_f32 v[84:85], v[84:85], v[128:129] op_sel_hi:[1,0]
	v_pk_mul_f32 v[86:87], v[86:87], v[128:129] op_sel_hi:[1,0]
	v_pk_mul_f32 v[136:137], v[76:77], v[128:129] op_sel_hi:[1,0]
	v_pk_mul_f32 v[128:129], v[78:79], v[128:129] op_sel_hi:[1,0]
	s_nop 0
	v_pk_fma_f32 v[74:75], v[86:87], v[100:101], v[114:115]
	s_nop 0
	v_pk_fma_f32 v[78:79], v[82:83], v[104:105], v[118:119]
	v_pk_fma_f32 v[76:77], v[80:81], v[102:103], v[116:117]
	s_nop 0
	v_pk_fma_f32 v[82:83], v[134:135], v[108:109], v[122:123]
	v_pk_fma_f32 v[80:81], v[132:133], v[106:107], v[120:121]
	v_pk_fma_f32 v[72:73], v[84:85], v[98:99], v[96:97]
	s_nop 0
	v_pk_fma_f32 v[86:87], v[128:129], v[112:113], v[126:127]
	v_pk_fma_f32 v[84:85], v[136:137], v[110:111], v[124:125]
	global_store_dwordx4 v[130:131], v[80:83], off
	global_store_dwordx4 v[130:131], v[84:87], off offset:1024
	global_store_dwordx4 v[130:131], v[76:79], off offset:2048
	global_store_dwordx4 v[130:131], v[72:75], off offset:3072
.LBB0_1464:
	s_nop 1
	v_and_b32_e32 v73, 0xffff0000, v64
	v_and_b32_e32 v75, 0xffff0000, v65
	v_lshlrev_b32_e32 v72, 16, v64
	v_lshlrev_b32_e32 v74, 16, v65
	v_mul_f32_e32 v76, v73, v73
	v_mul_f32_e32 v77, v75, v75
	v_fmac_f32_e32 v76, v72, v72
	v_fmac_f32_e32 v77, v74, v74
	v_add_f32_e32 v80, v76, v77
	v_and_b32_e32 v77, 0xffff0000, v66
	v_and_b32_e32 v79, 0xffff0000, v67
	v_lshlrev_b32_e32 v76, 16, v66
	v_lshlrev_b32_e32 v78, 16, v67
	v_mul_f32_e32 v81, v77, v77
	v_mul_f32_e32 v82, v79, v79
	v_fmac_f32_e32 v81, v76, v76
	v_fmac_f32_e32 v82, v78, v78
	v_add_f32_e32 v81, v81, v82
	v_add_f32_e32 v84, v81, v80
	v_and_b32_e32 v81, 0xffff0000, v68
	v_and_b32_e32 v83, 0xffff0000, v69
	v_lshlrev_b32_e32 v80, 16, v68
	v_lshlrev_b32_e32 v82, 16, v69
	v_mul_f32_e32 v85, v81, v81
	v_mul_f32_e32 v86, v83, v83
	v_fmac_f32_e32 v85, v80, v80
	v_fmac_f32_e32 v86, v82, v82
	v_add_f32_e32 v85, v85, v86
	v_add_f32_e32 v95, v85, v84
	v_and_b32_e32 v85, 0xffff0000, v70
	v_and_b32_e32 v87, 0xffff0000, v71
	v_lshlrev_b32_e32 v84, 16, v70
	v_lshlrev_b32_e32 v86, 16, v71
	s_waitcnt lgkmcnt(0)
	v_mul_f32_e32 v96, v85, v85
	v_mul_f32_e32 v97, v87, v87
	v_fmac_f32_e32 v96, v84, v84
	v_fmac_f32_e32 v97, v86, v86
	v_add_f32_e32 v96, v96, v97
	v_add_f32_e32 v95, v96, v95
	ds_bpermute_b32 v96, v88, v95
	s_and_b64 vcc, exec, s[0:1]
	s_waitcnt lgkmcnt(0)
	v_add_f32_e32 v95, v95, v96
	ds_bpermute_b32 v96, v89, v95
	s_waitcnt lgkmcnt(0)
	v_add_f32_e32 v95, v95, v96
	ds_bpermute_b32 v96, v90, v95
	s_waitcnt lgkmcnt(0)
	v_add_f32_e32 v95, v95, v96
	ds_bpermute_b32 v96, v91, v95
	s_waitcnt lgkmcnt(0)
	v_add_f32_e32 v95, v95, v96
	ds_bpermute_b32 v96, v92, v95
	s_waitcnt lgkmcnt(0)
	v_add_f32_e32 v95, v95, v96
	ds_bpermute_b32 v96, v93, v95
	s_cbranch_vccnz .LBB0_1452
	s_waitcnt lgkmcnt(0)
	v_add_f32_e32 v95, v95, v96
	v_fmamk_f32 v95, v95, 0x3a800000, v94
	v_rsq_f32_e32 v128, v95
	s_ashr_i32 s7, s6, 31
	v_lshlrev_b32_e32 v116, 16, v12
	v_and_b32_e32 v117, 0xffff0000, v12
	v_lshlrev_b32_e32 v118, 16, v13
	v_and_b32_e32 v119, 0xffff0000, v13
	v_lshlrev_b32_e32 v120, 16, v8
	v_and_b32_e32 v121, 0xffff0000, v8
	v_lshlrev_b32_e32 v122, 16, v9
	v_and_b32_e32 v123, 0xffff0000, v9
	s_lshl_b64 s[0:1], s[6:7], 12
	v_pk_mul_f32 v[80:81], v[80:81], v[128:129] op_sel_hi:[1,0]
	v_pk_mul_f32 v[82:83], v[82:83], v[128:129] op_sel_hi:[1,0]
	v_pk_mul_f32 v[132:133], v[72:73], v[128:129] op_sel_hi:[1,0]
	v_pk_mul_f32 v[134:135], v[74:75], v[128:129] op_sel_hi:[1,0]
	v_lshlrev_b32_e32 v96, 16, v14
	v_and_b32_e32 v97, 0xffff0000, v14
	v_lshlrev_b32_e32 v114, 16, v15
	v_and_b32_e32 v115, 0xffff0000, v15
	v_lshlrev_b32_e32 v124, 16, v10
	v_and_b32_e32 v125, 0xffff0000, v10
	v_lshlrev_b32_e32 v126, 16, v11
	v_and_b32_e32 v127, 0xffff0000, v11
	v_lshl_add_u64 v[130:131], v[40:41], 0, s[0:1]
	v_pk_mul_f32 v[84:85], v[84:85], v[128:129] op_sel_hi:[1,0]
	v_pk_mul_f32 v[86:87], v[86:87], v[128:129] op_sel_hi:[1,0]
	v_pk_mul_f32 v[136:137], v[76:77], v[128:129] op_sel_hi:[1,0]
	v_pk_mul_f32 v[128:129], v[78:79], v[128:129] op_sel_hi:[1,0]
	s_nop 0
	v_pk_fma_f32 v[74:75], v[86:87], v[100:101], v[114:115]
	s_nop 0
	v_pk_fma_f32 v[78:79], v[82:83], v[104:105], v[118:119]
	v_pk_fma_f32 v[76:77], v[80:81], v[102:103], v[116:117]
	s_nop 0
	v_pk_fma_f32 v[82:83], v[134:135], v[108:109], v[122:123]
	v_pk_fma_f32 v[80:81], v[132:133], v[106:107], v[120:121]
	v_pk_fma_f32 v[72:73], v[84:85], v[98:99], v[96:97]
	s_nop 0
	v_pk_fma_f32 v[86:87], v[128:129], v[112:113], v[126:127]
	v_pk_fma_f32 v[84:85], v[136:137], v[110:111], v[124:125]
	global_store_dwordx4 v[130:131], v[80:83], off
	global_store_dwordx4 v[130:131], v[84:87], off offset:1024
	global_store_dwordx4 v[130:131], v[76:79], off offset:2048
	global_store_dwordx4 v[130:131], v[72:75], off offset:3072
	s_branch .LBB0_1452
